# v14 plus: pb+4 work rebalanced: the 16 workgroups holding a 9th DeltaNet chunk-local item skip the S5 end-state items, the other 240 workgroups share them
# speedup vs baseline: 1.0218x; 1.0086x over previous
.LBB0_697:
	v_readlane_b32 s2, v253, 0
	s_nop 0
	s_add_i32 s10, s2, 0x800
	s_cmp_lt_u32 s2, 16
	s_cselect_b32 s10, 0x1020, s10
	s_cmpk_gt_u32 s10, 0x101f
	s_cbranch_scc1 .LBB0_962
	v_ashrrev_i32_e32 v28, 6, v60
	v_add_u32_e32 v60, 0xffffbf80, v28
	v_lshl_add_u32 v29, s10, 3, v60
	v_readlane_b32 s2, v255, 24
	v_mov_b32_e32 v0, 0x48000
	v_and_b32_e32 v61, 31, v29
	v_mov_b32_e32 v6, v160
	v_mad_i64_i32 v[0:1], s[2:3], s2, v0, v[2:3]
	s_mov_b64 s[2:3], 0x1ec32000
	v_and_b32_e32 v7, 63, v6
	v_lshlrev_b32_e32 v4, 9, v61
	v_lshl_add_u64 v[50:51], v[0:1], 0, s[2:3]
	v_lshl_or_b32 v162, v7, 3, v4
	v_lshl_add_u64 v[4:5], v[50:51], 0, v[162:163]
	global_load_dwordx2 v[54:55], v[4:5], off
	s_mov_b64 s[2:3], 0x1ec3a000
	v_lshl_add_u64 v[52:53], v[0:1], 0, s[2:3]
	v_lshlrev_b32_e32 v0, 11, v61
	v_lshlrev_b32_e32 v1, 6, v6
	s_movk_i32 s2, 0x400
	v_and_or_b32 v4, v1, s2, v0
	v_lshlrev_b32_e32 v0, 1, v6
	v_and_b32_e32 v5, 30, v0
	v_or_b32_e32 v0, v4, v5
	v_lshlrev_b32_e32 v162, 2, v0
	v_cmp_gt_u32_e32 vcc, 32, v7
	v_lshl_add_u64 v[0:1], v[52:53], 0, v[162:163]
	v_mov_b32_e32 v20, 0
	v_mov_b32_e32 v24, 0
	s_and_saveexec_b64 s[2:3], vcc
	s_cbranch_execz .LBB0_700
	global_load_dword v164, v[0:1], off

.LBB0_957:
	s_or_b64 exec, exec, s[2:3]
	v_readlane_b32 s2, v253, 1
	v_readlane_b32 s3, v253, 2
	s_load_dword s2, s[2:3], 0x0
	s_waitcnt vmcnt(1)
	v_mov_b64_e32 v[32:33], v[40:41]
	s_waitcnt vmcnt(0)
	v_mov_b64_e32 v[36:37], v[44:45]
	v_mov_b64_e32 v[34:35], v[42:43]
	v_mov_b64_e32 v[38:39], v[46:47]
	s_waitcnt lgkmcnt(0)
	s_add_i32 s10, s2, s10
	s_add_i32 s10, s10, -16
	s_cmpk_gt_i32 s10, 0x101f
	s_cselect_b64 s[2:3], -1, 0
	s_and_b64 vcc, exec, s[2:3]
	s_cbranch_vccnz .LBB0_959
	v_lshl_add_u32 v36, s10, 3, v60
	v_ashrrev_i32_e32 v32, 5, v36
	s_mov_b32 s4, 0xfe03f81
	v_mul_hi_i32 v33, v32, s4
	v_lshrrev_b32_e32 v34, 31, v33
	v_ashrrev_i32_e32 v33, 4, v33
	v_add_u32_e32 v33, v33, v34
	v_mul_i32_i24_e32 v34, 0x102, v33
	v_sub_u32_e32 v32, v32, v34
	v_mul_hi_i32_i24_e32 v35, 0x4080, v33
	v_mul_i32_i24_e32 v34, 0x4080, v33
	v_ashrrev_i32_e32 v33, 31, v32
	v_lshlrev_b64 v[32:33], 6, v[32:33]
	v_mov_b32_e32 v37, v160
	v_lshl_add_u64 v[32:33], v[34:35], 0, v[32:33]
	s_nop 0
	v_and_or_b32 v32, v37, 63, v32
	v_mad_u64_u32 v[34:35], s[4:5], v32, s97, v[48:49]
	v_mov_b32_e32 v32, v35
	v_mad_u64_u32 v[32:33], s[4:5], v33, s97, v[32:33]
	v_mov_b32_e32 v35, v32
	v_lshlrev_b32_e32 v32, 5, v36
	v_and_b32_e32 v162, 0x3e0, v32
	v_lshl_add_u64 v[36:37], v[34:35], 0, v[162:163]
	global_load_dwordx4 v[32:35], v[36:37], off offset:3600
	s_nop 0
	global_load_dwordx4 v[36:39], v[36:37], off offset:3584
